# memory K/V GEMM epilogue de-serialised: all row-statistics loads issued up front, per-row-group vmcnt(0) drains removed
# speedup vs baseline: 1.0014x; 1.0014x over previous
.LBB0_168:
	s_lshl_b64 s[0:1], s[0:1], 21
	s_add_u32 s0, s94, s0
	s_addc_u32 s1, s95, s1
	s_add_u32 s6, s0, 0x11400000
	s_addc_u32 s7, s1, 0
	s_add_u32 s10, s0, 0x11800000
	s_addc_u32 s11, s1, 0
	s_add_u32 s8, s0, 0x11c00000
	s_addc_u32 s9, s1, 0
	s_add_u32 s12, s94, 0x12400000
	s_addc_u32 s13, s95, 0
	s_lshr_b32 s0, s22, 1
	s_lshl_b32 s1, s21, 8
	v_ashrrev_i32_e32 v128, 4, v144
	s_add_i32 s1, s1, s26
	s_lshl_b32 s0, s0, 8
	v_add_u32_e32 v130, s1, v140
	v_ashrrev_i32_e32 v131, 31, v130
	v_lshlrev_b32_e32 v128, 3, v128
	v_lshlrev_b64 v[132:133], 8, v[130:131]
	v_ashrrev_i32_e32 v129, 31, v128
	v_lshl_add_u64 v[132:133], s[12:13], 0, v[132:133]
	v_lshl_add_u64 v[132:133], v[128:129], 2, v[132:133]
	global_load_dwordx4 v[146:149], v[132:133], off
	global_load_dwordx4 v[150:153], v[132:133], off offset:16
	s_mov_b64 s[98:99], 0x1000
	s_mov_b64 s[100:101], 0x5000
	v_lshl_add_u64 v[154:155], v[132:133], 0, s[98:99]
	global_load_dwordx4 v[176:179], v[154:155], off
	global_load_dwordx4 v[180:183], v[154:155], off offset:16
	v_lshl_add_u64 v[154:155], v[154:155], 0, s[98:99]
	global_load_dwordx4 v[184:187], v[154:155], off
	global_load_dwordx4 v[188:191], v[154:155], off offset:16
	v_lshl_add_u64 v[154:155], v[154:155], 0, s[98:99]
	global_load_dwordx4 v[192:195], v[154:155], off
	global_load_dwordx4 v[196:199], v[154:155], off offset:16
	v_lshl_add_u64 v[154:155], v[154:155], 0, s[100:101]
	global_load_dwordx4 v[200:203], v[154:155], off
	global_load_dwordx4 v[204:207], v[154:155], off offset:16
	v_lshl_add_u64 v[154:155], v[154:155], 0, s[98:99]
	global_load_dwordx4 v[208:211], v[154:155], off
	global_load_dwordx4 v[212:215], v[154:155], off offset:16
	v_lshl_add_u64 v[154:155], v[154:155], 0, s[98:99]
	global_load_dwordx4 v[216:219], v[154:155], off
	global_load_dwordx4 v[220:223], v[154:155], off offset:16
	v_lshl_add_u64 v[154:155], v[154:155], 0, s[98:99]
	global_load_dwordx4 v[224:227], v[154:155], off
	global_load_dwordx4 v[228:231], v[154:155], off offset:16
	v_mbcnt_lo_u32_b32 v131, -1, 0
	v_mbcnt_hi_u32_b32 v131, -1, v131
	v_and_b32_e32 v135, 64, v131
	v_xor_b32_e32 v134, 16, v131
	v_add_u32_e32 v135, 64, v135
	v_cmp_lt_i32_e32 vcc, v134, v135
	v_xor_b32_e32 v136, 32, v131
	v_mov_b32_e32 v132, 0x358637bd
	v_cndmask_b32_e32 v134, v131, v134, vcc
	v_cmp_lt_i32_e32 vcc, v136, v135
	v_lshlrev_b32_e32 v137, 2, v134
	v_lshlrev_b32_e32 v142, 1, v130
	v_cndmask_b32_e32 v131, v131, v136, vcc
	v_lshlrev_b32_e32 v136, 2, v131
	v_lshrrev_b32_e32 v131, 2, v140
	s_or_b32 s0, s0, s20
	v_and_b32_e32 v143, 0xe3, v130
	s_movk_i32 s1, 0x7ff
	v_ashrrev_i32_e32 v141, 8, v130
	v_mov_b32_e32 v133, 0
	v_lshlrev_b32_e32 v140, 2, v141
	s_waitcnt vmcnt(0)
	v_mov_b32_e32 v134, v147
	v_mov_b32_e32 v135, v148
	v_mov_b32_e32 v147, v149
	v_mov_b32_e32 v138, v152
	v_mov_b32_e32 v139, v150
	v_mov_b32_e32 v150, v153
	v_pk_add_f32 v[134:135], v[134:135], v[146:147]
	v_pk_add_f32 v[138:139], v[138:139], v[150:151]
	v_add_f32_e32 v134, v134, v135
	v_add_f32_e32 v134, v134, v139
	v_add_f32_e32 v134, v138, v134
	v_mov_b32_e32 v135, v134
	s_nop 1
	v_permlane16_swap_b32_e32 v135, v134
	v_and_b32_e32 v138, 4, v131
	v_add_u32_e32 v131, s0, v128
	v_and_b32_e32 v139, 0xff, v130
	v_cmp_lt_i32_e32 vcc, s1, v131
	s_waitcnt lgkmcnt(0)
	v_add_f32_e32 v134, v134, v135
	ds_bpermute_b32 v135, v136, v134
	s_waitcnt lgkmcnt(0)
	v_add_f32_e32 v134, v134, v135
	v_fmac_f32_e32 v132, 0x3a000000, v134
	v_rsq_f32_e32 v134, v132
	v_and_b32_e32 v132, 24, v142
	v_or3_b32 v132, v143, v132, v138
	v_pk_mul_f32 v[124:125], v[124:125], v[134:135] op_sel_hi:[1,0]
	v_pk_mul_f32 v[142:143], v[122:123], v[134:135] op_sel_hi:[1,0]
	v_pk_mul_f32 v[122:123], v[120:121], v[134:135] op_sel_hi:[1,0]
	v_cvt_pk_bf16_f32 v120, v124, v125
	v_lshlrev_b32_e32 v124, 1, v132
	v_pk_mul_f32 v[126:127], v[126:127], v[134:135] op_sel_hi:[1,0]
	s_nop 0
	v_cvt_pk_bf16_f32 v121, v126, v127
	v_cvt_pk_bf16_f32 v122, v122, v123
	v_cvt_pk_bf16_f32 v123, v142, v143
	s_and_saveexec_b64 s[0:1], vcc
	s_xor_b64 s[0:1], exec, s[0:1]
	s_cbranch_execz .LBB0_170
	v_add_u32_e32 v125, 0xfffff800, v131
	v_lshrrev_b32_e32 v125, 9, v125
	v_add_u32_e32 v125, v125, v140
	v_lshl_or_b32 v126, v125, 8, v139
	v_ashrrev_i32_e32 v127, 31, v126
	v_and_b32_e32 v135, 0x1f8, v131
	v_lshlrev_b64 v[126:127], 10, v[126:127]
	v_lshl_add_u64 v[126:127], s[10:11], 0, v[126:127]
	v_lshlrev_b32_e32 v132, 1, v135
	v_lshl_add_u64 v[126:127], v[126:127], 0, v[132:133]
	global_store_dwordx4 v[126:127], v[120:123], off
	v_lshl_or_b32 v126, v125, 9, v135
	v_ashrrev_i32_e32 v127, 31, v126
	v_lshlrev_b64 v[126:127], 9, v[126:127]
	v_lshl_add_u64 v[126:127], s[8:9], 0, v[126:127]
	v_mov_b32_e32 v125, v133
	v_lshl_add_u64 v[126:127], v[126:127], 0, v[124:125]
	global_store_short v[126:127], v120, off
	global_store_short_d16_hi v[126:127], v120, off offset:512
	global_store_short v[126:127], v121, off offset:1024
	global_store_short_d16_hi v[126:127], v121, off offset:1536
	global_store_short v[126:127], v122, off offset:2048
	global_store_short_d16_hi v[126:127], v122, off offset:2560
	global_store_short v[126:127], v123, off offset:3072
	global_store_short_d16_hi v[126:127], v123, off offset:3584

.LBB0_176:
	s_or_b64 exec, exec, s[0:1]
	v_add_u32_e32 v122, 16, v130
	v_ashrrev_i32_e32 v123, 31, v122
	v_lshlrev_b64 v[112:113], 8, v[122:123]
	v_lshl_add_u64 v[112:113], s[12:13], 0, v[112:113]
	v_lshl_add_u64 v[118:119], v[128:129], 2, v[112:113]
	v_mov_b32_e32 v112, v176
	v_mov_b32_e32 v113, v177
	v_mov_b32_e32 v114, v178
	v_mov_b32_e32 v115, v179
	v_mov_b32_e32 v118, v180
	v_mov_b32_e32 v119, v181
	v_mov_b32_e32 v120, v182
	v_mov_b32_e32 v121, v183
	v_and_b32_e32 v123, 0xe3, v122
	v_mov_b32_e32 v124, v113
	v_mov_b32_e32 v125, v114
	v_mov_b32_e32 v113, v115
	v_mov_b32_e32 v114, v120
	v_mov_b32_e32 v115, v118
	v_mov_b32_e32 v118, v121
	v_pk_add_f32 v[112:113], v[124:125], v[112:113]
	v_pk_add_f32 v[114:115], v[114:115], v[118:119]
	v_add_f32_e32 v112, v112, v113
	v_add_f32_e32 v112, v112, v115
	v_add_f32_e32 v112, v114, v112
	v_mov_b32_e32 v113, v112
	s_nop 1
	v_permlane16_swap_b32_e32 v113, v112
	v_mov_b32_e32 v114, 0x358637bd
	v_ashrrev_i32_e32 v120, 8, v122
	v_and_b32_e32 v118, 0xff, v122
	v_lshlrev_b32_e32 v121, 1, v122
	s_waitcnt lgkmcnt(0)
	v_add_f32_e32 v112, v112, v113
	v_mov_b32_e32 v113, v112
	s_nop 1
	v_permlane32_swap_b32_e32 v113, v112
	v_lshrrev_b32_e32 v122, 2, v122
	v_mov_b32_e32 v115, 0
	v_lshlrev_b32_e32 v119, 2, v120
	s_waitcnt lgkmcnt(0)
	v_add_f32_e32 v112, v112, v113
	v_fmac_f32_e32 v114, 0x3a000000, v112
	v_rsq_f32_e32 v112, v114
	v_and_b32_e32 v113, 24, v121
	v_and_b32_e32 v114, 4, v122
	v_or3_b32 v113, v114, v123, v113
	v_pk_mul_f32 v[108:109], v[108:109], v[112:113] op_sel_hi:[1,0]
	v_pk_mul_f32 v[122:123], v[106:107], v[112:113] op_sel_hi:[1,0]
	v_pk_mul_f32 v[106:107], v[104:105], v[112:113] op_sel_hi:[1,0]
	v_cvt_pk_bf16_f32 v104, v108, v109
	v_lshlrev_b32_e32 v108, 1, v113
	v_pk_mul_f32 v[110:111], v[110:111], v[112:113] op_sel_hi:[1,0]
	s_nop 0
	v_cvt_pk_bf16_f32 v105, v110, v111
	v_cvt_pk_bf16_f32 v106, v106, v107
	v_cvt_pk_bf16_f32 v107, v122, v123
	s_and_saveexec_b64 s[0:1], vcc
	s_xor_b64 s[0:1], exec, s[0:1]
	s_cbranch_execz .LBB0_178
	v_add_u32_e32 v109, 0xfffff800, v131
	v_lshrrev_b32_e32 v109, 9, v109
	v_add_u32_e32 v109, v119, v109
	v_lshl_or_b32 v110, v109, 8, v118
	v_ashrrev_i32_e32 v111, 31, v110
	v_and_b32_e32 v113, 0x1f8, v131
	v_lshlrev_b64 v[110:111], 10, v[110:111]
	v_lshl_add_u64 v[110:111], s[10:11], 0, v[110:111]
	v_lshlrev_b32_e32 v114, 1, v113
	v_lshl_add_u64 v[110:111], v[110:111], 0, v[114:115]
	global_store_dwordx4 v[110:111], v[104:107], off
	v_lshl_or_b32 v110, v109, 9, v113
	v_ashrrev_i32_e32 v111, 31, v110
	v_lshlrev_b64 v[110:111], 9, v[110:111]
	v_lshl_add_u64 v[110:111], s[8:9], 0, v[110:111]
	v_mov_b32_e32 v109, v115
	v_lshl_add_u64 v[110:111], v[110:111], 0, v[108:109]
	global_store_short v[110:111], v104, off
	global_store_short_d16_hi v[110:111], v104, off offset:512
	global_store_short v[110:111], v105, off offset:1024
	global_store_short_d16_hi v[110:111], v105, off offset:1536
	global_store_short v[110:111], v106, off offset:2048
	global_store_short_d16_hi v[110:111], v106, off offset:2560
	global_store_short v[110:111], v107, off offset:3072
	global_store_short_d16_hi v[110:111], v107, off offset:3584

.LBB0_184:
	s_or_b64 exec, exec, s[0:1]
	v_add_u32_e32 v104, 32, v130
	v_ashrrev_i32_e32 v105, 31, v104
	v_lshlrev_b64 v[96:97], 8, v[104:105]
	v_lshl_add_u64 v[96:97], s[12:13], 0, v[96:97]
	v_lshl_add_u64 v[106:107], v[128:129], 2, v[96:97]
	v_mov_b32_e32 v96, v184
	v_mov_b32_e32 v97, v185
	v_mov_b32_e32 v98, v186
	v_mov_b32_e32 v99, v187
	v_mov_b32_e32 v100, v188
	v_mov_b32_e32 v101, v189
	v_mov_b32_e32 v102, v190
	v_mov_b32_e32 v103, v191
	v_mov_b32_e32 v106, v97
	v_mov_b32_e32 v107, v98
	v_mov_b32_e32 v97, v99
	v_mov_b32_e32 v98, v102
	v_mov_b32_e32 v99, v100
	v_mov_b32_e32 v100, v103
	v_pk_add_f32 v[96:97], v[106:107], v[96:97]
	v_pk_add_f32 v[98:99], v[98:99], v[100:101]
	v_add_f32_e32 v96, v96, v97
	v_add_f32_e32 v96, v96, v99
	v_add_f32_e32 v96, v98, v96
	v_mov_b32_e32 v97, v96
	s_nop 1
	v_permlane16_swap_b32_e32 v97, v96
	v_mov_b32_e32 v98, 0x358637bd
	v_lshlrev_b32_e32 v103, 1, v104
	v_ashrrev_i32_e32 v102, 8, v104
	v_and_b32_e32 v100, 0xff, v104
	s_waitcnt lgkmcnt(0)
	v_add_f32_e32 v96, v96, v97
	v_mov_b32_e32 v97, v96
	s_nop 1
	v_permlane32_swap_b32_e32 v97, v96
	v_and_b32_e32 v104, 0xe3, v104
	v_mov_b32_e32 v99, 0
	v_lshlrev_b32_e32 v101, 2, v102
	s_waitcnt lgkmcnt(0)
	v_add_f32_e32 v96, v96, v97
	v_fmac_f32_e32 v98, 0x3a000000, v96
	v_rsq_f32_e32 v96, v98
	v_and_b32_e32 v97, 24, v103
	v_or3_b32 v97, v104, v97, v138
	v_pk_mul_f32 v[92:93], v[92:93], v[96:97] op_sel_hi:[1,0]
	v_pk_mul_f32 v[104:105], v[90:91], v[96:97] op_sel_hi:[1,0]
	v_pk_mul_f32 v[90:91], v[88:89], v[96:97] op_sel_hi:[1,0]
	v_cvt_pk_bf16_f32 v88, v92, v93
	v_lshlrev_b32_e32 v92, 1, v97
	v_pk_mul_f32 v[94:95], v[94:95], v[96:97] op_sel_hi:[1,0]
	s_nop 0
	v_cvt_pk_bf16_f32 v89, v94, v95
	v_cvt_pk_bf16_f32 v90, v90, v91
	v_cvt_pk_bf16_f32 v91, v104, v105
	s_and_saveexec_b64 s[0:1], vcc
	s_xor_b64 s[0:1], exec, s[0:1]
	s_cbranch_execz .LBB0_186
	v_add_u32_e32 v93, 0xfffff800, v131
	v_lshrrev_b32_e32 v93, 9, v93
	v_add_u32_e32 v93, v101, v93
	v_lshl_or_b32 v94, v93, 8, v100
	v_ashrrev_i32_e32 v95, 31, v94
	v_and_b32_e32 v97, 0x1f8, v131
	v_lshlrev_b64 v[94:95], 10, v[94:95]
	v_lshl_add_u64 v[94:95], s[10:11], 0, v[94:95]
	v_lshlrev_b32_e32 v98, 1, v97
	v_lshl_add_u64 v[94:95], v[94:95], 0, v[98:99]
	global_store_dwordx4 v[94:95], v[88:91], off
	v_lshl_or_b32 v94, v93, 9, v97
	v_ashrrev_i32_e32 v95, 31, v94
	v_lshlrev_b64 v[94:95], 9, v[94:95]
	v_lshl_add_u64 v[94:95], s[8:9], 0, v[94:95]
	v_mov_b32_e32 v93, v99
	v_lshl_add_u64 v[94:95], v[94:95], 0, v[92:93]
	global_store_short v[94:95], v88, off
	global_store_short_d16_hi v[94:95], v88, off offset:512
	global_store_short v[94:95], v89, off offset:1024
	global_store_short_d16_hi v[94:95], v89, off offset:1536
	global_store_short v[94:95], v90, off offset:2048
	global_store_short_d16_hi v[94:95], v90, off offset:2560
	global_store_short v[94:95], v91, off offset:3072
	global_store_short_d16_hi v[94:95], v91, off offset:3584

.LBB0_192:
	s_or_b64 exec, exec, s[0:1]
	v_add_u32_e32 v88, 48, v130
	v_ashrrev_i32_e32 v89, 31, v88
	v_lshlrev_b64 v[80:81], 8, v[88:89]
	v_lshl_add_u64 v[80:81], s[12:13], 0, v[80:81]
	v_lshl_add_u64 v[90:91], v[128:129], 2, v[80:81]
	v_mov_b32_e32 v80, v192
	v_mov_b32_e32 v81, v193
	v_mov_b32_e32 v82, v194
	v_mov_b32_e32 v83, v195
	v_mov_b32_e32 v84, v196
	v_mov_b32_e32 v85, v197
	v_mov_b32_e32 v86, v198
	v_mov_b32_e32 v87, v199
	v_and_b32_e32 v89, 0xe3, v88
	v_mov_b32_e32 v90, v81
	v_mov_b32_e32 v91, v82
	v_mov_b32_e32 v81, v83
	v_mov_b32_e32 v82, v86
	v_mov_b32_e32 v83, v84
	v_mov_b32_e32 v84, v87
	v_pk_add_f32 v[80:81], v[90:91], v[80:81]
	v_pk_add_f32 v[82:83], v[82:83], v[84:85]
	v_add_f32_e32 v80, v80, v81
	v_add_f32_e32 v80, v80, v83
	v_add_f32_e32 v80, v82, v80
	v_mov_b32_e32 v81, v80
	s_nop 1
	v_permlane16_swap_b32_e32 v81, v80
	v_mov_b32_e32 v82, 0x358637bd
	v_ashrrev_i32_e32 v86, 8, v88
	v_and_b32_e32 v84, 0xff, v88
	v_lshlrev_b32_e32 v87, 1, v88
	s_waitcnt lgkmcnt(0)
	v_add_f32_e32 v80, v80, v81
	v_mov_b32_e32 v81, v80
	s_nop 1
	v_permlane32_swap_b32_e32 v81, v80
	v_lshrrev_b32_e32 v88, 2, v88
	v_mov_b32_e32 v83, 0
	v_lshlrev_b32_e32 v85, 2, v86
	s_waitcnt lgkmcnt(0)
	v_add_f32_e32 v80, v80, v81
	v_fmac_f32_e32 v82, 0x3a000000, v80
	v_rsq_f32_e32 v80, v82
	v_and_b32_e32 v81, 24, v87
	v_and_b32_e32 v82, 4, v88
	v_or3_b32 v81, v82, v89, v81
	v_pk_mul_f32 v[76:77], v[76:77], v[80:81] op_sel_hi:[1,0]
	v_pk_mul_f32 v[88:89], v[74:75], v[80:81] op_sel_hi:[1,0]
	v_pk_mul_f32 v[74:75], v[72:73], v[80:81] op_sel_hi:[1,0]
	v_cvt_pk_bf16_f32 v72, v76, v77
	v_lshlrev_b32_e32 v76, 1, v81
	v_pk_mul_f32 v[78:79], v[78:79], v[80:81] op_sel_hi:[1,0]
	s_nop 0
	v_cvt_pk_bf16_f32 v73, v78, v79
	v_cvt_pk_bf16_f32 v74, v74, v75
	v_cvt_pk_bf16_f32 v75, v88, v89
	s_and_saveexec_b64 s[0:1], vcc
	s_xor_b64 s[0:1], exec, s[0:1]
	s_cbranch_execz .LBB0_194
	v_add_u32_e32 v77, 0xfffff800, v131
	v_lshrrev_b32_e32 v77, 9, v77
	v_add_u32_e32 v77, v85, v77
	v_lshl_or_b32 v78, v77, 8, v84
	v_ashrrev_i32_e32 v79, 31, v78
	v_and_b32_e32 v81, 0x1f8, v131
	v_lshlrev_b64 v[78:79], 10, v[78:79]
	v_lshl_add_u64 v[78:79], s[10:11], 0, v[78:79]
	v_lshlrev_b32_e32 v82, 1, v81
	v_lshl_add_u64 v[78:79], v[78:79], 0, v[82:83]
	global_store_dwordx4 v[78:79], v[72:75], off
	v_lshl_or_b32 v78, v77, 9, v81
	v_ashrrev_i32_e32 v79, 31, v78
	v_lshlrev_b64 v[78:79], 9, v[78:79]
	v_lshl_add_u64 v[78:79], s[8:9], 0, v[78:79]
	v_mov_b32_e32 v77, v83
	v_lshl_add_u64 v[78:79], v[78:79], 0, v[76:77]
	global_store_short v[78:79], v72, off
	global_store_short_d16_hi v[78:79], v72, off offset:512
	global_store_short v[78:79], v73, off offset:1024
	global_store_short_d16_hi v[78:79], v73, off offset:1536
	global_store_short v[78:79], v74, off offset:2048
	global_store_short_d16_hi v[78:79], v74, off offset:2560
	global_store_short v[78:79], v75, off offset:3072
	global_store_short_d16_hi v[78:79], v75, off offset:3584

.LBB0_200:
	s_or_b64 exec, exec, s[0:1]
	v_add_u32_e32 v72, 0x80, v130
	v_ashrrev_i32_e32 v73, 31, v72
	v_lshlrev_b64 v[64:65], 8, v[72:73]
	v_lshl_add_u64 v[64:65], s[12:13], 0, v[64:65]
	v_lshl_add_u64 v[74:75], v[128:129], 2, v[64:65]
	v_mov_b32_e32 v64, v200
	v_mov_b32_e32 v65, v201
	v_mov_b32_e32 v66, v202
	v_mov_b32_e32 v67, v203
	v_mov_b32_e32 v68, v204
	v_mov_b32_e32 v69, v205
	v_mov_b32_e32 v70, v206
	v_mov_b32_e32 v71, v207
	v_mov_b32_e32 v74, v65
	v_mov_b32_e32 v75, v66
	v_mov_b32_e32 v65, v67
	v_mov_b32_e32 v66, v70
	v_mov_b32_e32 v67, v68
	v_mov_b32_e32 v68, v71
	v_pk_add_f32 v[64:65], v[74:75], v[64:65]
	v_pk_add_f32 v[66:67], v[66:67], v[68:69]
	v_add_f32_e32 v64, v64, v65
	v_add_f32_e32 v64, v64, v67
	v_add_f32_e32 v64, v66, v64
	v_mov_b32_e32 v65, v64
	s_nop 1
	v_permlane16_swap_b32_e32 v65, v64
	v_mov_b32_e32 v66, 0x358637bd
	v_lshlrev_b32_e32 v71, 1, v72
	v_ashrrev_i32_e32 v70, 8, v72
	v_and_b32_e32 v68, 0xff, v72
	s_waitcnt lgkmcnt(0)
	v_add_f32_e32 v64, v64, v65
	v_mov_b32_e32 v65, v64
	s_nop 1
	v_permlane32_swap_b32_e32 v65, v64
	v_and_b32_e32 v72, 0xe3, v72
	v_mov_b32_e32 v67, 0
	v_lshlrev_b32_e32 v69, 2, v70
	s_waitcnt lgkmcnt(0)
	v_add_f32_e32 v64, v64, v65
	v_fmac_f32_e32 v66, 0x3a000000, v64
	v_rsq_f32_e32 v64, v66
	v_and_b32_e32 v65, 24, v71
	v_or3_b32 v65, v72, v65, v138
	v_pk_mul_f32 v[60:61], v[60:61], v[64:65] op_sel_hi:[1,0]
	v_pk_mul_f32 v[72:73], v[58:59], v[64:65] op_sel_hi:[1,0]
	v_pk_mul_f32 v[58:59], v[56:57], v[64:65] op_sel_hi:[1,0]
	v_cvt_pk_bf16_f32 v56, v60, v61
	v_lshlrev_b32_e32 v60, 1, v65
	v_pk_mul_f32 v[62:63], v[62:63], v[64:65] op_sel_hi:[1,0]
	s_nop 0
	v_cvt_pk_bf16_f32 v57, v62, v63
	v_cvt_pk_bf16_f32 v58, v58, v59
	v_cvt_pk_bf16_f32 v59, v72, v73
	s_and_saveexec_b64 s[0:1], vcc
	s_xor_b64 s[0:1], exec, s[0:1]
	s_cbranch_execz .LBB0_202
	v_add_u32_e32 v61, 0xfffff800, v131
	v_lshrrev_b32_e32 v61, 9, v61
	v_add_u32_e32 v61, v69, v61
	v_lshl_or_b32 v62, v61, 8, v68
	v_ashrrev_i32_e32 v63, 31, v62
	v_and_b32_e32 v65, 0x1f8, v131
	v_lshlrev_b64 v[62:63], 10, v[62:63]
	v_lshl_add_u64 v[62:63], s[10:11], 0, v[62:63]
	v_lshlrev_b32_e32 v66, 1, v65
	v_lshl_add_u64 v[62:63], v[62:63], 0, v[66:67]
	global_store_dwordx4 v[62:63], v[56:59], off
	v_lshl_or_b32 v62, v61, 9, v65
	v_ashrrev_i32_e32 v63, 31, v62
	v_lshlrev_b64 v[62:63], 9, v[62:63]
	v_lshl_add_u64 v[62:63], s[8:9], 0, v[62:63]
	v_mov_b32_e32 v61, v67
	v_lshl_add_u64 v[62:63], v[62:63], 0, v[60:61]
	global_store_short v[62:63], v56, off
	global_store_short_d16_hi v[62:63], v56, off offset:512
	global_store_short v[62:63], v57, off offset:1024
	global_store_short_d16_hi v[62:63], v57, off offset:1536
	global_store_short v[62:63], v58, off offset:2048
	global_store_short_d16_hi v[62:63], v58, off offset:2560
	global_store_short v[62:63], v59, off offset:3072
	global_store_short_d16_hi v[62:63], v59, off offset:3584

.LBB0_208:
	s_or_b64 exec, exec, s[0:1]
	v_add_u32_e32 v56, 0x90, v130
	v_ashrrev_i32_e32 v57, 31, v56
	v_lshlrev_b64 v[48:49], 8, v[56:57]
	v_lshl_add_u64 v[48:49], s[12:13], 0, v[48:49]
	v_lshl_add_u64 v[58:59], v[128:129], 2, v[48:49]
	v_mov_b32_e32 v48, v208
	v_mov_b32_e32 v49, v209
	v_mov_b32_e32 v50, v210
	v_mov_b32_e32 v51, v211
	v_mov_b32_e32 v52, v212
	v_mov_b32_e32 v53, v213
	v_mov_b32_e32 v54, v214
	v_mov_b32_e32 v55, v215
	v_and_b32_e32 v57, 0xe3, v56
	v_mov_b32_e32 v58, v49
	v_mov_b32_e32 v59, v50
	v_mov_b32_e32 v49, v51
	v_mov_b32_e32 v50, v54
	v_mov_b32_e32 v51, v52
	v_mov_b32_e32 v52, v55
	v_pk_add_f32 v[48:49], v[58:59], v[48:49]
	v_pk_add_f32 v[50:51], v[50:51], v[52:53]
	v_add_f32_e32 v48, v48, v49
	v_add_f32_e32 v48, v48, v51
	v_add_f32_e32 v48, v50, v48
	v_mov_b32_e32 v49, v48
	s_nop 1
	v_permlane16_swap_b32_e32 v49, v48
	v_mov_b32_e32 v50, 0x358637bd
	v_ashrrev_i32_e32 v54, 8, v56
	v_and_b32_e32 v52, 0xff, v56
	v_lshlrev_b32_e32 v55, 1, v56
	s_waitcnt lgkmcnt(0)
	v_add_f32_e32 v48, v48, v49
	v_mov_b32_e32 v49, v48
	s_nop 1
	v_permlane32_swap_b32_e32 v49, v48
	v_lshrrev_b32_e32 v56, 2, v56
	v_mov_b32_e32 v51, 0
	v_lshlrev_b32_e32 v53, 2, v54
	s_waitcnt lgkmcnt(0)
	v_add_f32_e32 v48, v48, v49
	v_fmac_f32_e32 v50, 0x3a000000, v48
	v_rsq_f32_e32 v48, v50
	v_and_b32_e32 v49, 24, v55
	v_and_b32_e32 v50, 4, v56
	v_or3_b32 v49, v50, v57, v49
	v_pk_mul_f32 v[44:45], v[44:45], v[48:49] op_sel_hi:[1,0]
	v_pk_mul_f32 v[56:57], v[42:43], v[48:49] op_sel_hi:[1,0]
	v_pk_mul_f32 v[42:43], v[40:41], v[48:49] op_sel_hi:[1,0]
	v_cvt_pk_bf16_f32 v40, v44, v45
	v_lshlrev_b32_e32 v44, 1, v49
	v_pk_mul_f32 v[46:47], v[46:47], v[48:49] op_sel_hi:[1,0]
	s_nop 0
	v_cvt_pk_bf16_f32 v41, v46, v47
	v_cvt_pk_bf16_f32 v42, v42, v43
	v_cvt_pk_bf16_f32 v43, v56, v57
	s_and_saveexec_b64 s[0:1], vcc
	s_xor_b64 s[0:1], exec, s[0:1]
	s_cbranch_execz .LBB0_210
	v_add_u32_e32 v45, 0xfffff800, v131
	v_lshrrev_b32_e32 v45, 9, v45
	v_add_u32_e32 v45, v53, v45
	v_lshl_or_b32 v46, v45, 8, v52
	v_ashrrev_i32_e32 v47, 31, v46
	v_and_b32_e32 v49, 0x1f8, v131
	v_lshlrev_b64 v[46:47], 10, v[46:47]
	v_lshl_add_u64 v[46:47], s[10:11], 0, v[46:47]
	v_lshlrev_b32_e32 v50, 1, v49
	v_lshl_add_u64 v[46:47], v[46:47], 0, v[50:51]
	global_store_dwordx4 v[46:47], v[40:43], off
	v_lshl_or_b32 v46, v45, 9, v49
	v_ashrrev_i32_e32 v47, 31, v46
	v_lshlrev_b64 v[46:47], 9, v[46:47]
	v_lshl_add_u64 v[46:47], s[8:9], 0, v[46:47]
	v_mov_b32_e32 v45, v51
	v_lshl_add_u64 v[46:47], v[46:47], 0, v[44:45]
	global_store_short v[46:47], v40, off
	global_store_short_d16_hi v[46:47], v40, off offset:512
	global_store_short v[46:47], v41, off offset:1024
	global_store_short_d16_hi v[46:47], v41, off offset:1536
	global_store_short v[46:47], v42, off offset:2048
	global_store_short_d16_hi v[46:47], v42, off offset:2560
	global_store_short v[46:47], v43, off offset:3072
	global_store_short_d16_hi v[46:47], v43, off offset:3584

.LBB0_216:
	s_or_b64 exec, exec, s[0:1]
	v_add_u32_e32 v40, 0xa0, v130
	v_ashrrev_i32_e32 v41, 31, v40
	v_lshlrev_b64 v[32:33], 8, v[40:41]
	v_lshl_add_u64 v[32:33], s[12:13], 0, v[32:33]
	v_lshl_add_u64 v[42:43], v[128:129], 2, v[32:33]
	v_mov_b32_e32 v32, v216
	v_mov_b32_e32 v33, v217
	v_mov_b32_e32 v34, v218
	v_mov_b32_e32 v35, v219
	v_mov_b32_e32 v36, v220
	v_mov_b32_e32 v37, v221
	v_mov_b32_e32 v38, v222
	v_mov_b32_e32 v39, v223
	v_mov_b32_e32 v42, v33
	v_mov_b32_e32 v43, v34
	v_mov_b32_e32 v33, v35
	v_mov_b32_e32 v34, v38
	v_mov_b32_e32 v35, v36
	v_mov_b32_e32 v36, v39
	v_pk_add_f32 v[32:33], v[42:43], v[32:33]
	v_pk_add_f32 v[34:35], v[34:35], v[36:37]
	v_add_f32_e32 v32, v32, v33
	v_add_f32_e32 v32, v32, v35
	v_add_f32_e32 v32, v34, v32
	v_mov_b32_e32 v33, v32
	s_nop 1
	v_permlane16_swap_b32_e32 v33, v32
	v_mov_b32_e32 v34, 0x358637bd
	v_lshlrev_b32_e32 v39, 1, v40
	v_ashrrev_i32_e32 v38, 8, v40
	v_and_b32_e32 v36, 0xff, v40
	s_waitcnt lgkmcnt(0)
	v_add_f32_e32 v32, v32, v33
	v_mov_b32_e32 v33, v32
	s_nop 1
	v_permlane32_swap_b32_e32 v33, v32
	v_and_b32_e32 v40, 0xe3, v40
	v_mov_b32_e32 v35, 0
	v_lshlrev_b32_e32 v37, 2, v38
	s_waitcnt lgkmcnt(0)
	v_add_f32_e32 v32, v32, v33
	v_fmac_f32_e32 v34, 0x3a000000, v32
	v_rsq_f32_e32 v32, v34
	v_and_b32_e32 v33, 24, v39
	v_or3_b32 v33, v40, v33, v138
	v_pk_mul_f32 v[28:29], v[28:29], v[32:33] op_sel_hi:[1,0]
	v_pk_mul_f32 v[40:41], v[26:27], v[32:33] op_sel_hi:[1,0]
	v_pk_mul_f32 v[26:27], v[24:25], v[32:33] op_sel_hi:[1,0]
	v_cvt_pk_bf16_f32 v24, v28, v29
	v_lshlrev_b32_e32 v28, 1, v33
	v_pk_mul_f32 v[30:31], v[30:31], v[32:33] op_sel_hi:[1,0]
	s_nop 0
	v_cvt_pk_bf16_f32 v25, v30, v31
	v_cvt_pk_bf16_f32 v26, v26, v27
	v_cvt_pk_bf16_f32 v27, v40, v41
	s_and_saveexec_b64 s[0:1], vcc
	s_xor_b64 s[0:1], exec, s[0:1]
	s_cbranch_execz .LBB0_218
	v_add_u32_e32 v29, 0xfffff800, v131
	v_lshrrev_b32_e32 v29, 9, v29
	v_add_u32_e32 v29, v37, v29
	v_lshl_or_b32 v30, v29, 8, v36
	v_ashrrev_i32_e32 v31, 31, v30
	v_and_b32_e32 v33, 0x1f8, v131
	v_lshlrev_b64 v[30:31], 10, v[30:31]
	v_lshl_add_u64 v[30:31], s[10:11], 0, v[30:31]
	v_lshlrev_b32_e32 v34, 1, v33
	v_lshl_add_u64 v[30:31], v[30:31], 0, v[34:35]
	global_store_dwordx4 v[30:31], v[24:27], off
	v_lshl_or_b32 v30, v29, 9, v33
	v_ashrrev_i32_e32 v31, 31, v30
	v_lshlrev_b64 v[30:31], 9, v[30:31]
	v_lshl_add_u64 v[30:31], s[8:9], 0, v[30:31]
	v_mov_b32_e32 v29, v35
	v_lshl_add_u64 v[30:31], v[30:31], 0, v[28:29]
	global_store_short v[30:31], v24, off
	global_store_short_d16_hi v[30:31], v24, off offset:512
	global_store_short v[30:31], v25, off offset:1024
	global_store_short_d16_hi v[30:31], v25, off offset:1536
	global_store_short v[30:31], v26, off offset:2048
	global_store_short_d16_hi v[30:31], v26, off offset:2560
	global_store_short v[30:31], v27, off offset:3072
	global_store_short_d16_hi v[30:31], v27, off offset:3584

.LBB0_224:
	s_or_b64 exec, exec, s[0:1]
	v_add_u32_e32 v24, 0xb0, v130
	v_ashrrev_i32_e32 v25, 31, v24
	v_lshlrev_b64 v[16:17], 8, v[24:25]
	v_lshl_add_u64 v[16:17], s[12:13], 0, v[16:17]
	v_lshl_add_u64 v[26:27], v[128:129], 2, v[16:17]
	v_mov_b32_e32 v16, v224
	v_mov_b32_e32 v17, v225
	v_mov_b32_e32 v18, v226
	v_mov_b32_e32 v19, v227
	v_mov_b32_e32 v20, v228
	v_mov_b32_e32 v21, v229
	v_mov_b32_e32 v22, v230
	v_mov_b32_e32 v23, v231
	v_and_b32_e32 v25, 0xe3, v24
	v_mov_b32_e32 v26, v17
	v_mov_b32_e32 v27, v18
	v_mov_b32_e32 v17, v19
	v_mov_b32_e32 v18, v22
	v_mov_b32_e32 v19, v20
	v_mov_b32_e32 v20, v23
	v_pk_add_f32 v[16:17], v[26:27], v[16:17]
	v_pk_add_f32 v[18:19], v[18:19], v[20:21]
	v_add_f32_e32 v16, v16, v17
	v_add_f32_e32 v16, v16, v19
	v_add_f32_e32 v16, v18, v16
	v_mov_b32_e32 v17, v16
	s_nop 1
	v_permlane16_swap_b32_e32 v17, v16
	v_mov_b32_e32 v18, 0x358637bd
	v_ashrrev_i32_e32 v22, 8, v24
	v_and_b32_e32 v20, 0xff, v24
	v_lshlrev_b32_e32 v23, 1, v24
	s_waitcnt lgkmcnt(0)
	v_add_f32_e32 v16, v16, v17
	v_mov_b32_e32 v17, v16
	s_nop 1
	v_permlane32_swap_b32_e32 v17, v16
	v_lshrrev_b32_e32 v24, 2, v24
	v_mov_b32_e32 v19, 0
	v_lshlrev_b32_e32 v21, 2, v22
	s_waitcnt lgkmcnt(0)
	v_add_f32_e32 v16, v16, v17
	v_fmac_f32_e32 v18, 0x3a000000, v16
	v_rsq_f32_e32 v16, v18
	v_and_b32_e32 v17, 24, v23
	v_and_b32_e32 v18, 4, v24
	v_or3_b32 v17, v18, v25, v17
	v_pk_mul_f32 v[12:13], v[12:13], v[16:17] op_sel_hi:[1,0]
	v_pk_mul_f32 v[24:25], v[10:11], v[16:17] op_sel_hi:[1,0]
	v_pk_mul_f32 v[10:11], v[8:9], v[16:17] op_sel_hi:[1,0]
	v_cvt_pk_bf16_f32 v8, v12, v13
	v_lshlrev_b32_e32 v12, 1, v17
	v_pk_mul_f32 v[14:15], v[14:15], v[16:17] op_sel_hi:[1,0]
	s_nop 0
	v_cvt_pk_bf16_f32 v9, v14, v15
	v_cvt_pk_bf16_f32 v10, v10, v11
	v_cvt_pk_bf16_f32 v11, v24, v25
	s_and_saveexec_b64 s[0:1], vcc
	s_xor_b64 s[0:1], exec, s[0:1]
	s_cbranch_execz .LBB0_226
	v_add_u32_e32 v13, 0xfffff800, v131
	v_lshrrev_b32_e32 v13, 9, v13
	v_add_u32_e32 v13, v21, v13
	v_lshl_or_b32 v14, v13, 8, v20
	v_ashrrev_i32_e32 v15, 31, v14
	v_and_b32_e32 v17, 0x1f8, v131
	v_lshlrev_b64 v[14:15], 10, v[14:15]
	v_lshl_add_u64 v[14:15], s[10:11], 0, v[14:15]
	v_lshlrev_b32_e32 v18, 1, v17
	v_lshl_add_u64 v[14:15], v[14:15], 0, v[18:19]
	global_store_dwordx4 v[14:15], v[8:11], off
	v_lshl_or_b32 v14, v13, 9, v17
	v_ashrrev_i32_e32 v15, 31, v14
	v_lshlrev_b64 v[14:15], 9, v[14:15]
	v_lshl_add_u64 v[14:15], s[8:9], 0, v[14:15]
	v_mov_b32_e32 v13, v19
	v_lshl_add_u64 v[14:15], v[14:15], 0, v[12:13]
	global_store_short v[14:15], v8, off
	global_store_short_d16_hi v[14:15], v8, off offset:512
	global_store_short v[14:15], v9, off offset:1024
	global_store_short_d16_hi v[14:15], v9, off offset:1536
	global_store_short v[14:15], v10, off offset:2048
	global_store_short_d16_hi v[14:15], v10, off offset:2560
	global_store_short v[14:15], v11, off offset:3072
	global_store_short_d16_hi v[14:15], v11, off offset:3584
